# GEMM K-loop heads, CMP K-loop and ATTN k-loop head aligned to 64 bytes
# baseline (speedup 1.0000x reference)
.LBB0_190:
	s_mov_b32 s61, s52
	s_add_i32 s52, s52, 1
	s_mov_b32 s59, s14
	s_lshr_b32 s14, s52, 3
	s_mul_i32 s14, s14, s48
	s_add_i32 s14, s14, s41
	s_cmp_lt_i32 s14, 32
	s_mov_b32 s60, s18
	s_cselect_b64 s[30:31], -1, 0
	s_lshl_b32 s18, s14, 3
	s_and_b32 s18, s18, 24
	s_add_i32 s18, s18, s42
	s_and_b32 s15, s52, 7
	s_lshl_b32 s18, s18, 3
	s_or_b32 s18, s18, s15
	s_ashr_i32 s19, s18, 31
	s_mov_b64 s[34:35], s[20:21]
	s_ashr_i32 s14, s14, 2
	s_lshl_b64 s[20:21], s[18:19], 19
	s_mov_b64 s[8:9], s[22:23]
	s_add_u32 s22, s64, s20
	s_addc_u32 s23, s65, s21
	s_and_b64 s[20:21], s[30:31], exec
	s_cselect_b32 s62, s23, s9
	s_cselect_b32 s63, s22, s8
	s_ashr_i32 s15, s14, 31
	s_lshl_b64 s[20:21], s[14:15], 19
	v_readlane_b32 s36, v235, 29
	v_readlane_b32 s37, v235, 30
	s_add_u32 s20, s36, s20
	s_addc_u32 s21, s37, s21
	s_and_b64 s[36:37], s[30:31], exec
	s_cselect_b32 s15, s21, s35
	s_cselect_b32 s67, s20, s34
	s_add_u32 s68, s34, 0x100
	v_mov_b32_e32 v60, 0
	s_addc_u32 s69, s35, 0
	s_mov_b32 s70, -2
	v_mov_b32_e32 v61, v60
	v_mov_b64_e32 v[62:63], 0
	v_mov_b64_e32 v[68:69], 0
	v_mov_b64_e32 v[70:71], 0
	v_mov_b64_e32 v[80:81], 0
	v_mov_b64_e32 v[82:83], 0
	v_mov_b64_e32 v[88:89], 0
	v_mov_b64_e32 v[90:91], 0
	v_mov_b64_e32 v[0:1], 0
	v_mov_b64_e32 v[2:3], 0
	v_mov_b64_e32 v[32:33], 0
	v_mov_b64_e32 v[34:35], 0
	v_mov_b64_e32 v[4:5], 0
	v_mov_b64_e32 v[6:7], 0
	v_mov_b64_e32 v[36:37], 0
	v_mov_b64_e32 v[38:39], 0
	v_mov_b64_e32 v[76:77], 0
	v_mov_b64_e32 v[78:79], 0
	v_mov_b64_e32 v[84:85], 0
	v_mov_b64_e32 v[86:87], 0
	v_mov_b64_e32 v[92:93], 0
	v_mov_b64_e32 v[94:95], 0
	v_mov_b64_e32 v[96:97], 0
	v_mov_b64_e32 v[98:99], 0
	v_mov_b64_e32 v[8:9], 0
	v_mov_b64_e32 v[10:11], 0
	v_mov_b64_e32 v[40:41], 0
	v_mov_b64_e32 v[42:43], 0
	v_mov_b64_e32 v[12:13], 0
	v_mov_b64_e32 v[14:15], 0
	v_mov_b64_e32 v[44:45], 0
	v_mov_b64_e32 v[46:47], 0
	v_mov_b64_e32 v[100:101], 0
	v_mov_b64_e32 v[102:103], 0
	v_mov_b64_e32 v[104:105], 0
	v_mov_b64_e32 v[106:107], 0
	v_mov_b64_e32 v[108:109], 0
	v_mov_b64_e32 v[110:111], 0
	v_mov_b64_e32 v[112:113], 0
	v_mov_b64_e32 v[114:115], 0
	v_mov_b64_e32 v[16:17], 0
	v_mov_b64_e32 v[18:19], 0
	v_mov_b64_e32 v[52:53], 0
	v_mov_b64_e32 v[54:55], 0
	v_mov_b64_e32 v[20:21], 0
	v_mov_b64_e32 v[22:23], 0
	v_mov_b64_e32 v[56:57], 0
	v_mov_b64_e32 v[58:59], 0
	v_mov_b64_e32 v[116:117], 0
	v_mov_b64_e32 v[118:119], 0
	v_mov_b64_e32 v[120:121], 0
	v_mov_b64_e32 v[122:123], 0
	v_mov_b64_e32 v[124:125], 0
	v_mov_b64_e32 v[126:127], 0
	v_mov_b64_e32 v[128:129], 0
	v_mov_b64_e32 v[130:131], 0
	v_mov_b64_e32 v[24:25], 0
	v_mov_b64_e32 v[26:27], 0
	v_mov_b64_e32 v[64:65], 0
	v_mov_b64_e32 v[66:67], 0
	v_mov_b64_e32 v[28:29], 0
	v_mov_b64_e32 v[30:31], 0
	v_mov_b64_e32 v[72:73], 0
	v_mov_b64_e32 v[74:75], 0
	v_readlane_b32 s38, v235, 31
	v_readlane_b32 s39, v235, 32
	.p2align	6

.LBB0_285:
	s_ashr_i32 s23, s22, 31
	v_cmp_lt_i64_e32 vcc, s[24:25], v[144:145]
	s_lshl_b64 s[24:25], s[22:23], 19
	s_add_u32 s24, s64, s24
	s_addc_u32 s25, s65, s25
	s_and_b64 s[28:29], vcc, exec
	s_cselect_b32 s23, s25, s35
	s_cselect_b32 s55, s24, s34
	s_ashr_i32 s21, s20, 31
	s_lshl_b64 s[28:29], s[20:21], 19
	s_add_u32 s28, s42, s28
	s_addc_u32 s29, s43, s29
	s_and_b64 s[38:39], vcc, exec
	s_cselect_b32 s21, s29, s37
	s_cselect_b32 s56, s28, s36
	s_add_u32 s34, s34, 0x40080
	s_addc_u32 s35, s35, 0
	s_add_u32 s57, s36, 0x100
	v_mov_b32_e32 v0, 0
	s_addc_u32 s58, s37, 0
	s_mov_b32 s59, -2
	v_mov_b32_e32 v1, v0
	v_mov_b32_e32 v2, v0
	v_mov_b32_e32 v3, v0
	v_mov_b32_e32 v4, v0
	v_mov_b32_e32 v5, v0
	v_mov_b32_e32 v6, v0
	v_mov_b32_e32 v7, v0
	s_waitcnt lgkmcnt(0)
	v_mov_b64_e32 v[16:17], 0
	v_mov_b64_e32 v[18:19], 0
	v_mov_b64_e32 v[20:21], 0
	v_mov_b64_e32 v[22:23], 0
	v_mov_b64_e32 v[32:33], 0
	v_mov_b64_e32 v[34:35], 0
	v_mov_b64_e32 v[36:37], 0
	v_mov_b64_e32 v[38:39], 0
	v_mov_b64_e32 v[48:49], 0
	v_mov_b64_e32 v[50:51], 0
	v_mov_b64_e32 v[52:53], 0
	v_mov_b64_e32 v[54:55], 0
	v_mov_b64_e32 v[8:9], 0
	v_mov_b64_e32 v[10:11], 0
	v_mov_b64_e32 v[12:13], 0
	v_mov_b64_e32 v[14:15], 0
	v_mov_b64_e32 v[24:25], 0
	v_mov_b64_e32 v[26:27], 0
	v_mov_b64_e32 v[28:29], 0
	v_mov_b64_e32 v[30:31], 0
	v_mov_b64_e32 v[40:41], 0
	v_mov_b64_e32 v[42:43], 0
	v_mov_b64_e32 v[44:45], 0
	v_mov_b64_e32 v[46:47], 0
	v_mov_b64_e32 v[56:57], 0
	v_mov_b64_e32 v[58:59], 0
	v_mov_b64_e32 v[60:61], 0
	v_mov_b64_e32 v[62:63], 0
	v_mov_b64_e32 v[64:65], 0
	v_mov_b64_e32 v[66:67], 0
	v_mov_b64_e32 v[68:69], 0
	v_mov_b64_e32 v[70:71], 0
	v_mov_b64_e32 v[80:81], 0
	v_mov_b64_e32 v[82:83], 0
	v_mov_b64_e32 v[84:85], 0
	v_mov_b64_e32 v[86:87], 0
	v_mov_b64_e32 v[96:97], 0
	v_mov_b64_e32 v[98:99], 0
	v_mov_b64_e32 v[100:101], 0
	v_mov_b64_e32 v[102:103], 0
	v_mov_b64_e32 v[112:113], 0
	v_mov_b64_e32 v[114:115], 0
	v_mov_b64_e32 v[116:117], 0
	v_mov_b64_e32 v[118:119], 0
	v_mov_b64_e32 v[72:73], 0
	v_mov_b64_e32 v[74:75], 0
	v_mov_b64_e32 v[76:77], 0
	v_mov_b64_e32 v[78:79], 0
	v_mov_b64_e32 v[88:89], 0
	v_mov_b64_e32 v[90:91], 0
	v_mov_b64_e32 v[92:93], 0
	v_mov_b64_e32 v[94:95], 0
	v_mov_b64_e32 v[104:105], 0
	v_mov_b64_e32 v[106:107], 0
	v_mov_b64_e32 v[108:109], 0
	v_mov_b64_e32 v[110:111], 0
	v_mov_b64_e32 v[120:121], 0
	v_mov_b64_e32 v[122:123], 0
	v_mov_b64_e32 v[124:125], 0
	v_mov_b64_e32 v[126:127], 0
	.p2align	6

.LBB0_363:
	s_ashr_i32 s13, s12, 31
	v_cmp_lt_i64_e32 vcc, s[14:15], v[190:191]
	s_lshl_b64 s[14:15], s[12:13], 19
	s_add_u32 s14, s26, s14
	s_addc_u32 s15, s27, s15
	s_and_b64 s[18:19], vcc, exec
	s_cselect_b32 s13, s15, s23
	s_cselect_b32 s21, s14, s22
	s_ashr_i32 s11, s10, 31
	s_lshl_b64 s[18:19], s[10:11], 19
	s_add_u32 s18, s31, s18
	s_addc_u32 s19, s34, s19
	s_and_b64 s[28:29], vcc, exec
	s_cselect_b32 s11, s19, s25
	s_cselect_b32 s48, s18, s24
	s_add_u32 s22, s22, 0x40080
	s_addc_u32 s23, s23, 0
	s_add_u32 s49, s24, 0x100
	v_mov_b32_e32 v0, 0
	s_addc_u32 s50, s25, 0
	s_mov_b32 s51, -2
	s_waitcnt lgkmcnt(0)
	v_mov_b32_e32 v1, v0
	v_mov_b32_e32 v2, v0
	v_mov_b32_e32 v3, v0
	v_mov_b32_e32 v4, v0
	v_mov_b32_e32 v5, v0
	v_mov_b32_e32 v6, v0
	v_mov_b32_e32 v7, v0
	s_waitcnt lgkmcnt(0)
	v_mov_b32_e32 v16, v0
	v_mov_b32_e32 v17, v0
	v_mov_b32_e32 v18, v0
	v_mov_b32_e32 v19, v0
	v_mov_b32_e32 v20, v0
	v_mov_b32_e32 v21, v0
	v_mov_b32_e32 v22, v0
	v_mov_b32_e32 v23, v0
	v_mov_b32_e32 v32, v0
	v_mov_b32_e32 v33, v0
	v_mov_b32_e32 v34, v0
	v_mov_b32_e32 v35, v0
	v_mov_b32_e32 v36, v0
	v_mov_b32_e32 v37, v0
	v_mov_b32_e32 v38, v0
	v_mov_b32_e32 v39, v0
	s_waitcnt vmcnt(0)
	v_mov_b64_e32 v[48:49], 0
	v_mov_b64_e32 v[50:51], 0
	v_mov_b64_e32 v[52:53], 0
	v_mov_b64_e32 v[54:55], 0
	v_mov_b64_e32 v[8:9], 0
	v_mov_b64_e32 v[10:11], 0
	v_mov_b64_e32 v[12:13], 0
	v_mov_b64_e32 v[14:15], 0
	v_mov_b64_e32 v[24:25], 0
	v_mov_b64_e32 v[26:27], 0
	v_mov_b64_e32 v[28:29], 0
	v_mov_b64_e32 v[30:31], 0
	v_mov_b64_e32 v[40:41], 0
	v_mov_b64_e32 v[42:43], 0
	v_mov_b64_e32 v[44:45], 0
	v_mov_b64_e32 v[46:47], 0
	v_mov_b64_e32 v[56:57], 0
	v_mov_b64_e32 v[58:59], 0
	v_mov_b64_e32 v[60:61], 0
	v_mov_b64_e32 v[62:63], 0
	v_mov_b64_e32 v[64:65], 0
	v_mov_b64_e32 v[66:67], 0
	v_mov_b64_e32 v[68:69], 0
	v_mov_b64_e32 v[70:71], 0
	v_mov_b64_e32 v[80:81], 0
	v_mov_b64_e32 v[82:83], 0
	v_mov_b64_e32 v[84:85], 0
	v_mov_b64_e32 v[86:87], 0
	v_mov_b64_e32 v[96:97], 0
	v_mov_b64_e32 v[98:99], 0
	v_mov_b64_e32 v[100:101], 0
	v_mov_b64_e32 v[102:103], 0
	v_mov_b64_e32 v[112:113], 0
	v_mov_b64_e32 v[114:115], 0
	v_mov_b64_e32 v[116:117], 0
	v_mov_b64_e32 v[118:119], 0
	v_mov_b64_e32 v[72:73], 0
	v_mov_b64_e32 v[74:75], 0
	v_mov_b64_e32 v[76:77], 0
	v_mov_b64_e32 v[78:79], 0
	v_mov_b64_e32 v[88:89], 0
	v_mov_b64_e32 v[90:91], 0
	v_mov_b64_e32 v[92:93], 0
	v_mov_b64_e32 v[94:95], 0
	v_mov_b64_e32 v[104:105], 0
	v_mov_b64_e32 v[106:107], 0
	v_mov_b64_e32 v[108:109], 0
	v_mov_b64_e32 v[110:111], 0
	v_mov_b64_e32 v[120:121], 0
	v_mov_b64_e32 v[122:123], 0
	v_mov_b64_e32 v[124:125], 0
	v_mov_b64_e32 v[126:127], 0
	.p2align	6

.LBB0_451:
	s_mov_b32 s62, s50
	s_add_i32 s50, s50, 1
	s_mov_b32 s60, s10
	s_lshr_b32 s10, s50, 3
	s_mul_i32 s10, s10, s51
	s_add_i32 s10, s10, s17
	s_cmpk_lt_i32 s10, 0x58
	s_mov_b32 s61, s12
	s_cselect_b64 s[30:31], -1, 0
	s_lshl_b32 s12, s10, 3
	s_and_b32 s12, s12, 24
	s_add_i32 s12, s12, s72
	s_and_b32 s11, s50, 7
	s_lshl_b32 s12, s12, 3
	s_or_b32 s12, s12, s11
	s_ashr_i32 s13, s12, 31
	s_mov_b64 s[34:35], s[14:15]
	s_ashr_i32 s10, s10, 2
	s_lshl_b64 s[14:15], s[12:13], 19
	s_mov_b64 s[8:9], s[18:19]
	s_add_u32 s18, s64, s14
	s_addc_u32 s19, s65, s15
	s_and_b64 s[14:15], s[30:31], exec
	s_cselect_b32 s63, s19, s9
	s_cselect_b32 s67, s18, s8
	s_ashr_i32 s11, s10, 31
	s_lshl_b64 s[14:15], s[10:11], 19
	s_add_u32 s14, s73, s14
	s_addc_u32 s15, s44, s15
	s_and_b64 s[36:37], s[30:31], exec
	s_cselect_b32 s11, s15, s35
	s_cselect_b32 s68, s14, s34
	s_add_u32 s69, s34, 0x100
	s_addc_u32 s70, s35, 0
	s_mov_b32 s71, -2
	v_mov_b64_e32 v[56:57], 0
	v_mov_b64_e32 v[58:59], 0
	v_mov_b64_e32 v[52:53], 0
	v_mov_b64_e32 v[54:55], 0
	v_mov_b64_e32 v[48:49], 0
	v_mov_b64_e32 v[50:51], 0
	v_mov_b64_e32 v[44:45], 0
	v_mov_b64_e32 v[46:47], 0
	v_mov_b64_e32 v[0:1], 0
	v_mov_b64_e32 v[2:3], 0
	v_mov_b64_e32 v[60:61], 0
	v_mov_b64_e32 v[62:63], 0
	v_mov_b64_e32 v[4:5], 0
	v_mov_b64_e32 v[6:7], 0
	v_mov_b64_e32 v[64:65], 0
	v_mov_b64_e32 v[66:67], 0
	v_mov_b64_e32 v[116:117], 0
	v_mov_b64_e32 v[118:119], 0
	v_mov_b64_e32 v[120:121], 0
	v_mov_b64_e32 v[122:123], 0
	v_mov_b64_e32 v[124:125], 0
	v_mov_b64_e32 v[126:127], 0
	v_mov_b64_e32 v[128:129], 0
	v_mov_b64_e32 v[130:131], 0
	v_mov_b64_e32 v[8:9], 0
	v_mov_b64_e32 v[10:11], 0
	v_mov_b64_e32 v[72:73], 0
	v_mov_b64_e32 v[74:75], 0
	v_mov_b64_e32 v[12:13], 0
	v_mov_b64_e32 v[14:15], 0
	v_mov_b64_e32 v[76:77], 0
	v_mov_b64_e32 v[78:79], 0
	v_mov_b64_e32 v[88:89], 0
	v_mov_b64_e32 v[90:91], 0
	v_mov_b64_e32 v[84:85], 0
	v_mov_b64_e32 v[86:87], 0
	v_mov_b64_e32 v[92:93], 0
	v_mov_b64_e32 v[94:95], 0
	v_mov_b64_e32 v[80:81], 0
	v_mov_b64_e32 v[82:83], 0
	v_mov_b64_e32 v[28:29], 0
	v_mov_b64_e32 v[30:31], 0
	v_mov_b64_e32 v[100:101], 0
	v_mov_b64_e32 v[102:103], 0
	v_mov_b64_e32 v[32:33], 0
	v_mov_b64_e32 v[34:35], 0
	v_mov_b64_e32 v[104:105], 0
	v_mov_b64_e32 v[106:107], 0
	v_mov_b64_e32 v[132:133], 0
	v_mov_b64_e32 v[134:135], 0
	v_mov_b64_e32 v[136:137], 0
	v_mov_b64_e32 v[138:139], 0
	v_mov_b64_e32 v[140:141], 0
	v_mov_b64_e32 v[142:143], 0
	v_mov_b64_e32 v[144:145], 0
	v_mov_b64_e32 v[146:147], 0
	v_mov_b64_e32 v[36:37], 0
	v_mov_b64_e32 v[38:39], 0
	v_mov_b64_e32 v[108:109], 0
	v_mov_b64_e32 v[110:111], 0
	v_mov_b64_e32 v[40:41], 0
	v_mov_b64_e32 v[42:43], 0
	v_mov_b64_e32 v[112:113], 0
	v_mov_b64_e32 v[114:115], 0
	.p2align	6

.LBB0_553:
	s_add_u32 s49, s18, 0x100
	v_mov_b32_e32 v0, 0
	s_addc_u32 s50, s19, 0
	s_mov_b32 s51, -2
	s_waitcnt lgkmcnt(0)
	v_mov_b32_e32 v1, v0
	v_mov_b64_e32 v[2:3], 0
	v_mov_b64_e32 v[4:5], 0
	v_mov_b64_e32 v[6:7], 0
	v_mov_b64_e32 v[16:17], 0
	v_mov_b64_e32 v[18:19], 0
	v_mov_b64_e32 v[20:21], 0
	v_mov_b64_e32 v[22:23], 0
	v_mov_b64_e32 v[32:33], 0
	v_mov_b64_e32 v[34:35], 0
	v_mov_b64_e32 v[36:37], 0
	v_mov_b64_e32 v[38:39], 0
	v_mov_b64_e32 v[48:49], 0
	v_mov_b64_e32 v[50:51], 0
	v_mov_b64_e32 v[52:53], 0
	v_mov_b64_e32 v[54:55], 0
	v_mov_b64_e32 v[8:9], 0
	v_mov_b64_e32 v[10:11], 0
	v_mov_b64_e32 v[12:13], 0
	v_mov_b64_e32 v[14:15], 0
	v_mov_b64_e32 v[24:25], 0
	v_mov_b64_e32 v[26:27], 0
	v_mov_b64_e32 v[28:29], 0
	v_mov_b64_e32 v[30:31], 0
	v_mov_b64_e32 v[40:41], 0
	v_mov_b64_e32 v[42:43], 0
	v_mov_b64_e32 v[44:45], 0
	v_mov_b64_e32 v[46:47], 0
	v_mov_b64_e32 v[56:57], 0
	v_mov_b64_e32 v[58:59], 0
	v_mov_b64_e32 v[60:61], 0
	v_mov_b64_e32 v[62:63], 0
	v_mov_b64_e32 v[64:65], 0
	v_mov_b64_e32 v[66:67], 0
	v_mov_b64_e32 v[68:69], 0
	v_mov_b64_e32 v[70:71], 0
	v_mov_b64_e32 v[80:81], 0
	v_mov_b64_e32 v[82:83], 0
	v_mov_b64_e32 v[84:85], 0
	v_mov_b64_e32 v[86:87], 0
	v_mov_b64_e32 v[96:97], 0
	v_mov_b64_e32 v[98:99], 0
	v_mov_b64_e32 v[100:101], 0
	v_mov_b64_e32 v[102:103], 0
	v_mov_b64_e32 v[112:113], 0
	v_mov_b64_e32 v[114:115], 0
	v_mov_b64_e32 v[116:117], 0
	v_mov_b64_e32 v[118:119], 0
	v_mov_b64_e32 v[72:73], 0
	v_mov_b64_e32 v[74:75], 0
	v_mov_b64_e32 v[76:77], 0
	v_mov_b64_e32 v[78:79], 0
	v_mov_b64_e32 v[88:89], 0
	v_mov_b64_e32 v[90:91], 0
	v_mov_b64_e32 v[92:93], 0
	v_mov_b64_e32 v[94:95], 0
	v_mov_b64_e32 v[104:105], 0
	v_mov_b64_e32 v[106:107], 0
	v_mov_b64_e32 v[108:109], 0
	v_mov_b64_e32 v[110:111], 0
	v_mov_b64_e32 v[120:121], 0
	v_mov_b64_e32 v[122:123], 0
	v_mov_b64_e32 v[124:125], 0
	v_mov_b64_e32 v[126:127], 0
	.p2align	6

.LBB0_641:
	s_ashr_i32 s29, s28, 31
	s_lshl_b64 s[30:31], s[28:29], 19
	s_add_u32 s30, s64, s30
	s_addc_u32 s31, s65, s31
	s_and_b64 s[34:35], s[8:9], exec
	s_cselect_b32 s42, s31, s7
	s_cselect_b32 s43, s30, s6
	s_ashr_i32 s23, s22, 31
	s_lshl_b64 s[34:35], s[22:23], 19
	s_add_u32 s34, s46, s34
	s_addc_u32 s35, s47, s35
	s_and_b64 s[40:41], s[8:9], exec
	s_cselect_b32 s23, s35, s39
	s_cselect_b32 s44, s34, s38
	s_add_u32 s6, s6, 0x40080
	s_addc_u32 s7, s7, 0
	s_add_u32 s45, s38, 0x100
	v_mov_b32_e32 v0, 0
	s_addc_u32 s67, s39, 0
	s_mov_b32 s68, -2
	s_waitcnt lgkmcnt(0)
	v_mov_b32_e32 v1, v0
	v_mov_b64_e32 v[2:3], 0
	v_mov_b64_e32 v[4:5], 0
	v_mov_b64_e32 v[6:7], 0
	v_mov_b64_e32 v[16:17], 0
	v_mov_b64_e32 v[18:19], 0
	v_mov_b64_e32 v[20:21], 0
	v_mov_b64_e32 v[22:23], 0
	v_mov_b64_e32 v[40:41], 0
	v_mov_b64_e32 v[42:43], 0
	v_mov_b64_e32 v[44:45], 0
	v_mov_b64_e32 v[46:47], 0
	v_mov_b64_e32 v[56:57], 0
	v_mov_b64_e32 v[58:59], 0
	v_mov_b64_e32 v[60:61], 0
	v_mov_b64_e32 v[62:63], 0
	v_mov_b64_e32 v[8:9], 0
	v_mov_b64_e32 v[10:11], 0
	v_mov_b64_e32 v[12:13], 0
	v_mov_b64_e32 v[14:15], 0
	v_mov_b64_e32 v[32:33], 0
	v_mov_b64_e32 v[34:35], 0
	v_mov_b64_e32 v[36:37], 0
	v_mov_b64_e32 v[38:39], 0
	v_mov_b64_e32 v[48:49], 0
	v_mov_b64_e32 v[50:51], 0
	v_mov_b64_e32 v[52:53], 0
	v_mov_b64_e32 v[54:55], 0
	v_mov_b64_e32 v[64:65], 0
	v_mov_b64_e32 v[66:67], 0
	v_mov_b64_e32 v[68:69], 0
	v_mov_b64_e32 v[70:71], 0
	v_mov_b64_e32 v[72:73], 0
	v_mov_b64_e32 v[74:75], 0
	v_mov_b64_e32 v[76:77], 0
	v_mov_b64_e32 v[78:79], 0
	v_mov_b64_e32 v[88:89], 0
	v_mov_b64_e32 v[90:91], 0
	v_mov_b64_e32 v[92:93], 0
	v_mov_b64_e32 v[94:95], 0
	v_mov_b64_e32 v[104:105], 0
	v_mov_b64_e32 v[106:107], 0
	v_mov_b64_e32 v[108:109], 0
	v_mov_b64_e32 v[110:111], 0
	v_mov_b64_e32 v[120:121], 0
	v_mov_b64_e32 v[122:123], 0
	v_mov_b64_e32 v[124:125], 0
	v_mov_b64_e32 v[126:127], 0
	v_mov_b64_e32 v[80:81], 0
	v_mov_b64_e32 v[82:83], 0
	v_mov_b64_e32 v[84:85], 0
	v_mov_b64_e32 v[86:87], 0
	v_mov_b64_e32 v[96:97], 0
	v_mov_b64_e32 v[98:99], 0
	v_mov_b64_e32 v[100:101], 0
	v_mov_b64_e32 v[102:103], 0
	v_mov_b64_e32 v[112:113], 0
	v_mov_b64_e32 v[114:115], 0
	v_mov_b64_e32 v[116:117], 0
	v_mov_b64_e32 v[118:119], 0
	v_mov_b64_e32 v[128:129], 0
	v_mov_b64_e32 v[130:131], 0
	v_mov_b64_e32 v[132:133], 0
	v_mov_b64_e32 v[134:135], 0
	.p2align	6

.LBB0_869:
	s_lshl_b64 s[28:29], s[20:21], 20
	s_add_u32 s28, s39, s28
	s_addc_u32 s29, s40, s29
	s_and_b64 s[0:1], s[0:1], exec
	s_cselect_b32 s21, s29, s37
	s_cselect_b32 s31, s28, s36
	s_add_u32 s71, s36, 0x100
	v_mov_b32_e32 v0, 0
	s_addc_u32 s78, s37, 0
	s_mov_b32 s79, -2
	v_mov_b32_e32 v1, v0
	v_mov_b64_e32 v[2:3], 0
	v_mov_b64_e32 v[4:5], 0
	v_mov_b64_e32 v[6:7], 0
	v_mov_b64_e32 v[12:13], 0
	v_mov_b64_e32 v[14:15], 0
	v_mov_b64_e32 v[20:21], 0
	v_mov_b64_e32 v[22:23], 0
	v_mov_b64_e32 v[24:25], 0
	v_mov_b64_e32 v[26:27], 0
	v_mov_b64_e32 v[28:29], 0
	v_mov_b64_e32 v[30:31], 0
	v_mov_b64_e32 v[32:33], 0
	v_mov_b64_e32 v[34:35], 0
	v_mov_b64_e32 v[36:37], 0
	v_mov_b64_e32 v[38:39], 0
	v_mov_b64_e32 v[40:41], 0
	v_mov_b64_e32 v[42:43], 0
	v_mov_b64_e32 v[44:45], 0
	v_mov_b64_e32 v[46:47], 0
	v_mov_b64_e32 v[48:49], 0
	v_mov_b64_e32 v[50:51], 0
	v_mov_b64_e32 v[52:53], 0
	v_mov_b64_e32 v[54:55], 0
	v_mov_b64_e32 v[56:57], 0
	v_mov_b64_e32 v[58:59], 0
	v_mov_b64_e32 v[60:61], 0
	v_mov_b64_e32 v[62:63], 0
	v_mov_b64_e32 v[64:65], 0
	v_mov_b64_e32 v[66:67], 0
	v_mov_b64_e32 v[68:69], 0
	v_mov_b64_e32 v[70:71], 0
	s_branch .LBB0_871
	.p2align	6

.LBB0_1449:
	s_add_i32 s6, s45, 1
	s_max_i32 s2, s45, 8
	s_lshl_b32 s0, s6, 1
	s_sub_i32 s8, s0, s2
	s_mul_i32 s1, s50, 0x600000
	s_mul_hi_i32 s0, s50, 0x600000
	s_add_u32 s1, s24, s1
	s_addc_u32 s3, s25, s0
	s_lshl_b32 s0, s40, 1
	s_add_u32 s0, s1, s0
	s_addc_u32 s1, s3, 0
	v_lshl_add_u64 v[0:1], s[0:1], 0, v[112:113]
	v_mov_b32_e32 v121, v32
	v_lshl_add_u64 v[0:1], v[0:1], 0, v[120:121]
	s_waitcnt lgkmcnt(0)
	s_barrier
	ds_read_b32 v104, v194
	s_cmp_lt_i32 s8, -7
	s_waitcnt vmcnt(1)
	ds_write_b128 v195, v[236:239]
	s_waitcnt vmcnt(0)
	ds_write_b128 v195, v[240:243] offset:18432
	s_waitcnt lgkmcnt(0)
	s_barrier
	s_cbranch_scc1 .LBB0_1268
	v_lshl_add_u64 v[132:133], s[0:1], 0, v[120:121]
	s_add_i32 s0, s2, -8
	s_not_b32 s1, s45
	s_add_i32 s7, s0, s1
	s_lshl_b32 s1, s45, 1
	v_mov_b32_e32 v46, v32
	v_mov_b32_e32 v47, v32
	s_sub_i32 s9, s1, s2
	v_mov_b32_e32 v33, v32
	v_mov_b32_e32 v34, v32
	v_mov_b32_e32 v35, v32
	v_mov_b32_e32 v36, v32
	v_mov_b32_e32 v37, v32
	v_mov_b32_e32 v38, v32
	v_mov_b32_e32 v39, v32
	v_mov_b32_e32 v40, v32
	v_mov_b32_e32 v41, v32
	v_mov_b32_e32 v42, v32
	v_mov_b32_e32 v43, v32
	v_mov_b32_e32 v44, v32
	v_mov_b32_e32 v45, v32
	v_mov_b64_e32 v[78:79], v[46:47]
	v_mov_b64_e32 v[62:63], v[46:47]
	v_sub_u32_e32 v117, v130, v152
	s_add_i32 s8, s8, 7
	s_add_i32 s9, s9, 10
	s_sub_i32 s28, s0, s45
	s_mov_b32 s2, 0
	v_mov_b32_e32 v121, 0
	v_mov_b32_e32 v123, 0xff800000
	v_mov_b64_e32 v[76:77], v[44:45]
	v_mov_b64_e32 v[74:75], v[42:43]
	v_mov_b64_e32 v[72:73], v[40:41]
	v_mov_b64_e32 v[70:71], v[38:39]
	v_mov_b64_e32 v[68:69], v[36:37]
	v_mov_b64_e32 v[66:67], v[34:35]
	v_mov_b64_e32 v[64:65], v[32:33]
	v_mov_b64_e32 v[60:61], v[44:45]
	v_mov_b64_e32 v[58:59], v[42:43]
	v_mov_b64_e32 v[56:57], v[40:41]
	v_mov_b64_e32 v[54:55], v[38:39]
	v_mov_b64_e32 v[52:53], v[36:37]
	v_mov_b64_e32 v[50:51], v[34:35]
	v_mov_b64_e32 v[48:49], v[32:33]
	.p2align	6

.LBB0_1550:
	s_ashr_i32 s13, s12, 31
	v_cmp_lt_i64_e32 vcc, s[14:15], v[164:165]
	s_lshl_b64 s[14:15], s[12:13], 19
	s_add_u32 s14, s26, s14
	s_addc_u32 s15, s27, s15
	s_and_b64 s[16:17], vcc, exec
	s_cselect_b32 s13, s15, s21
	s_cselect_b32 s19, s14, s20
	s_ashr_i32 s11, s10, 31
	s_lshl_b64 s[16:17], s[10:11], 19
	s_add_u32 s16, s31, s16
	s_addc_u32 s17, s34, s17
	s_and_b64 s[28:29], vcc, exec
	s_cselect_b32 s11, s17, s23
	s_cselect_b32 s48, s16, s22
	s_add_u32 s20, s20, 0x40080
	s_addc_u32 s21, s21, 0
	s_add_u32 s49, s22, 0x100
	v_mov_b32_e32 v0, 0
	s_addc_u32 s50, s23, 0
	s_mov_b32 s51, -2
	s_waitcnt lgkmcnt(0)
	v_mov_b32_e32 v1, v0
	v_mov_b64_e32 v[2:3], 0
	v_mov_b64_e32 v[4:5], 0
	v_mov_b64_e32 v[6:7], 0
	v_mov_b64_e32 v[16:17], 0
	v_mov_b64_e32 v[18:19], 0
	v_mov_b64_e32 v[20:21], 0
	v_mov_b64_e32 v[22:23], 0
	v_mov_b64_e32 v[32:33], 0
	v_mov_b64_e32 v[34:35], 0
	v_mov_b64_e32 v[36:37], 0
	v_mov_b64_e32 v[38:39], 0
	v_mov_b64_e32 v[48:49], 0
	v_mov_b64_e32 v[50:51], 0
	v_mov_b64_e32 v[52:53], 0
	v_mov_b64_e32 v[54:55], 0
	v_mov_b64_e32 v[8:9], 0
	v_mov_b64_e32 v[10:11], 0
	v_mov_b64_e32 v[12:13], 0
	v_mov_b64_e32 v[14:15], 0
	v_mov_b64_e32 v[24:25], 0
	v_mov_b64_e32 v[26:27], 0
	v_mov_b64_e32 v[28:29], 0
	v_mov_b64_e32 v[30:31], 0
	v_mov_b64_e32 v[40:41], 0
	v_mov_b64_e32 v[42:43], 0
	v_mov_b64_e32 v[44:45], 0
	v_mov_b64_e32 v[46:47], 0
	v_mov_b64_e32 v[56:57], 0
	v_mov_b64_e32 v[58:59], 0
	v_mov_b64_e32 v[60:61], 0
	v_mov_b64_e32 v[62:63], 0
	v_mov_b64_e32 v[64:65], 0
	v_mov_b64_e32 v[66:67], 0
	v_mov_b64_e32 v[68:69], 0
	v_mov_b64_e32 v[70:71], 0
	v_mov_b64_e32 v[80:81], 0
	v_mov_b64_e32 v[82:83], 0
	v_mov_b64_e32 v[84:85], 0
	v_mov_b64_e32 v[86:87], 0
	v_mov_b64_e32 v[96:97], 0
	v_mov_b64_e32 v[98:99], 0
	v_mov_b64_e32 v[100:101], 0
	v_mov_b64_e32 v[102:103], 0
	v_mov_b64_e32 v[112:113], 0
	v_mov_b64_e32 v[114:115], 0
	v_mov_b64_e32 v[116:117], 0
	v_mov_b64_e32 v[118:119], 0
	v_mov_b64_e32 v[72:73], 0
	v_mov_b64_e32 v[74:75], 0
	v_mov_b64_e32 v[76:77], 0
	v_mov_b64_e32 v[78:79], 0
	v_mov_b64_e32 v[88:89], 0
	v_mov_b64_e32 v[90:91], 0
	v_mov_b64_e32 v[92:93], 0
	v_mov_b64_e32 v[94:95], 0
	v_mov_b64_e32 v[104:105], 0
	v_mov_b64_e32 v[106:107], 0
	v_mov_b64_e32 v[108:109], 0
	v_mov_b64_e32 v[110:111], 0
	v_mov_b64_e32 v[120:121], 0
	v_mov_b64_e32 v[122:123], 0
	v_mov_b64_e32 v[124:125], 0
	v_mov_b64_e32 v[126:127], 0
	.p2align	6

.LBB0_1638:
	s_mov_b32 s58, s46
	s_add_i32 s46, s46, 1
	s_mov_b32 s56, s10
	s_lshr_b32 s10, s46, 3
	s_mul_i32 s10, s10, s47
	s_add_i32 s10, s10, s37
	s_cmpk_lt_i32 s10, 0x58
	s_mov_b32 s57, s12
	s_cselect_b64 s[26:27], -1, 0
	s_lshl_b32 s12, s10, 3
	s_and_b32 s12, s12, 24
	s_add_i32 s12, s12, s38
	s_and_b32 s11, s46, 7
	s_lshl_b32 s12, s12, 3
	s_or_b32 s12, s12, s11
	s_ashr_i32 s13, s12, 31
	s_mov_b64 s[28:29], s[14:15]
	s_ashr_i32 s10, s10, 2
	s_lshl_b64 s[14:15], s[12:13], 19
	s_mov_b64 s[8:9], s[16:17]
	s_add_u32 s16, s64, s14
	s_addc_u32 s17, s65, s15
	s_and_b64 s[14:15], s[26:27], exec
	s_cselect_b32 s59, s17, s9
	s_cselect_b32 s60, s16, s8
	s_ashr_i32 s11, s10, 31
	s_lshl_b64 s[14:15], s[10:11], 19
	s_add_u32 s14, s39, s14
	s_addc_u32 s15, s40, s15
	s_and_b64 s[30:31], s[26:27], exec
	s_cselect_b32 s11, s15, s29
	s_cselect_b32 s61, s14, s28
	s_add_u32 s62, s28, 0x100
	s_addc_u32 s63, s29, 0
	s_mov_b32 s67, -2
	v_mov_b64_e32 v[56:57], 0
	v_mov_b64_e32 v[58:59], 0
	v_mov_b64_e32 v[52:53], 0
	v_mov_b64_e32 v[54:55], 0
	v_mov_b64_e32 v[48:49], 0
	v_mov_b64_e32 v[50:51], 0
	v_mov_b64_e32 v[44:45], 0
	v_mov_b64_e32 v[46:47], 0
	v_mov_b64_e32 v[0:1], 0
	v_mov_b64_e32 v[2:3], 0
	v_mov_b64_e32 v[60:61], 0
	v_mov_b64_e32 v[62:63], 0
	v_mov_b64_e32 v[4:5], 0
	v_mov_b64_e32 v[6:7], 0
	v_mov_b64_e32 v[64:65], 0
	v_mov_b64_e32 v[66:67], 0
	v_mov_b64_e32 v[116:117], 0
	v_mov_b64_e32 v[118:119], 0
	v_mov_b64_e32 v[120:121], 0
	v_mov_b64_e32 v[122:123], 0
	v_mov_b64_e32 v[124:125], 0
	v_mov_b64_e32 v[126:127], 0
	v_mov_b64_e32 v[128:129], 0
	v_mov_b64_e32 v[130:131], 0
	v_mov_b64_e32 v[8:9], 0
	v_mov_b64_e32 v[10:11], 0
	v_mov_b64_e32 v[72:73], 0
	v_mov_b64_e32 v[74:75], 0
	v_mov_b64_e32 v[12:13], 0
	v_mov_b64_e32 v[14:15], 0
	v_mov_b64_e32 v[76:77], 0
	v_mov_b64_e32 v[78:79], 0
	v_mov_b64_e32 v[88:89], 0
	v_mov_b64_e32 v[90:91], 0
	v_mov_b64_e32 v[84:85], 0
	v_mov_b64_e32 v[86:87], 0
	v_mov_b64_e32 v[92:93], 0
	v_mov_b64_e32 v[94:95], 0
	v_mov_b64_e32 v[80:81], 0
	v_mov_b64_e32 v[82:83], 0
	v_mov_b64_e32 v[28:29], 0
	v_mov_b64_e32 v[30:31], 0
	v_mov_b64_e32 v[100:101], 0
	v_mov_b64_e32 v[102:103], 0
	v_mov_b64_e32 v[32:33], 0
	v_mov_b64_e32 v[34:35], 0
	v_mov_b64_e32 v[104:105], 0
	v_mov_b64_e32 v[106:107], 0
	v_mov_b64_e32 v[132:133], 0
	v_mov_b64_e32 v[134:135], 0
	v_mov_b64_e32 v[136:137], 0
	v_mov_b64_e32 v[138:139], 0
	v_mov_b64_e32 v[140:141], 0
	v_mov_b64_e32 v[142:143], 0
	v_mov_b64_e32 v[144:145], 0
	v_mov_b64_e32 v[146:147], 0
	v_mov_b64_e32 v[36:37], 0
	v_mov_b64_e32 v[38:39], 0
	v_mov_b64_e32 v[108:109], 0
	v_mov_b64_e32 v[110:111], 0
	v_mov_b64_e32 v[40:41], 0
	v_mov_b64_e32 v[42:43], 0
	v_mov_b64_e32 v[112:113], 0
	v_mov_b64_e32 v[114:115], 0
	.p2align	6

.LBB0_1740:
	s_add_u32 s45, s16, 0x100
	v_mov_b32_e32 v0, 0
	s_addc_u32 s46, s17, 0
	s_mov_b32 s47, -2
	s_waitcnt lgkmcnt(0)
	v_mov_b32_e32 v1, v0
	v_mov_b64_e32 v[2:3], 0
	v_mov_b64_e32 v[4:5], 0
	v_mov_b64_e32 v[6:7], 0
	v_mov_b64_e32 v[16:17], 0
	v_mov_b64_e32 v[18:19], 0
	v_mov_b64_e32 v[20:21], 0
	v_mov_b64_e32 v[22:23], 0
	v_mov_b64_e32 v[32:33], 0
	v_mov_b64_e32 v[34:35], 0
	v_mov_b64_e32 v[36:37], 0
	v_mov_b64_e32 v[38:39], 0
	v_mov_b64_e32 v[48:49], 0
	v_mov_b64_e32 v[50:51], 0
	v_mov_b64_e32 v[52:53], 0
	v_mov_b64_e32 v[54:55], 0
	v_mov_b64_e32 v[8:9], 0
	v_mov_b64_e32 v[10:11], 0
	v_mov_b64_e32 v[12:13], 0
	v_mov_b64_e32 v[14:15], 0
	v_mov_b64_e32 v[24:25], 0
	v_mov_b64_e32 v[26:27], 0
	v_mov_b64_e32 v[28:29], 0
	v_mov_b64_e32 v[30:31], 0
	v_mov_b64_e32 v[40:41], 0
	v_mov_b64_e32 v[42:43], 0
	v_mov_b64_e32 v[44:45], 0
	v_mov_b64_e32 v[46:47], 0
	v_mov_b64_e32 v[56:57], 0
	v_mov_b64_e32 v[58:59], 0
	v_mov_b64_e32 v[60:61], 0
	v_mov_b64_e32 v[62:63], 0
	v_mov_b64_e32 v[64:65], 0
	v_mov_b64_e32 v[66:67], 0
	v_mov_b64_e32 v[68:69], 0
	v_mov_b64_e32 v[70:71], 0
	v_mov_b64_e32 v[80:81], 0
	v_mov_b64_e32 v[82:83], 0
	v_mov_b64_e32 v[84:85], 0
	v_mov_b64_e32 v[86:87], 0
	v_mov_b64_e32 v[96:97], 0
	v_mov_b64_e32 v[98:99], 0
	v_mov_b64_e32 v[100:101], 0
	v_mov_b64_e32 v[102:103], 0
	v_mov_b64_e32 v[112:113], 0
	v_mov_b64_e32 v[114:115], 0
	v_mov_b64_e32 v[116:117], 0
	v_mov_b64_e32 v[118:119], 0
	v_mov_b64_e32 v[72:73], 0
	v_mov_b64_e32 v[74:75], 0
	v_mov_b64_e32 v[76:77], 0
	v_mov_b64_e32 v[78:79], 0
	v_mov_b64_e32 v[88:89], 0
	v_mov_b64_e32 v[90:91], 0
	v_mov_b64_e32 v[92:93], 0
	v_mov_b64_e32 v[94:95], 0
	v_mov_b64_e32 v[104:105], 0
	v_mov_b64_e32 v[106:107], 0
	v_mov_b64_e32 v[108:109], 0
	v_mov_b64_e32 v[110:111], 0
	v_mov_b64_e32 v[120:121], 0
	v_mov_b64_e32 v[122:123], 0
	v_mov_b64_e32 v[124:125], 0
	v_mov_b64_e32 v[126:127], 0
	.p2align	6
